# latent-hyena pass C: iteration-2 data loads issued with iteration 1, iteration-3 loads issued at the start of iteration-2 compute (iterations 1-3 of 4; iteration 4 unchanged)
# speedup vs baseline: 1.0031x; 1.0031x over previous
.LBB0_838:
	s_or_b64 exec, exec, s[42:43]
	v_lshl_add_u64 v[2:3], v[94:95], 0, s[70:71]
	v_add_co_u32_e32 v2, vcc, 0x2000, v2
	s_waitcnt lgkmcnt(0)
	s_nop 0
	v_addc_co_u32_e32 v3, vcc, 0, v3, vcc
	s_barrier
	global_load_dwordx4 v[2:5], v[2:3], off offset:2048
	v_add_u32_e32 v34, s19, v0
	v_mov_b64_e32 v[36:37], s[6:7]
	v_mad_i64_i32 v[0:1], s[20:21], v34, s0, v[36:37]
	v_lshl_add_u64 v[0:1], v[0:1], 0, s[70:71]
	s_movk_i32 s23, 0x3000
	v_ashrrev_i32_e32 v35, 31, v34
	s_mov_b32 s22, 0xcc00000
	v_readlane_b32 s88, v253, 36
	v_readlane_b32 s89, v253, 37
	s_waitcnt vmcnt(1)
	v_lshl_add_u64 v[206:207], v[96:97], 0, s[70:71]
	v_add_co_u32_e32 v64, vcc, s3, v206
	s_nop 1
	v_addc_co_u32_e32 v65, vcc, 0, v207, vcc
	global_load_dwordx4 v[208:211], v[64:65], off offset:2048
	v_lshl_add_u64 v[214:215], v[98:99], 0, s[70:71]
	v_add_co_u32_e32 v66, vcc, s3, v214
	s_nop 1
	v_addc_co_u32_e32 v67, vcc, 0, v215, vcc
	global_load_dwordx4 v[216:219], v[66:67], off offset:2048
	v_add_co_u32_e32 v68, vcc, s23, v0
	s_nop 1
	v_addc_co_u32_e32 v69, vcc, 0, v1, vcc
	global_load_dwordx4 v[220:223], v[68:69], off
	global_load_dwordx4 v[224:227], v161, s[84:85] offset:2064
	global_load_dwordx4 v[18:21], v161, s[84:85] offset:2048
	global_load_dwordx4 v[228:231], v161, s[86:87] offset:2064
	global_load_dwordx4 v[22:25], v161, s[86:87] offset:2048
	global_load_dwordx4 v[26:29], v196, s[86:87]
	global_load_dwordx4 v[232:235], v197, s[86:87] offset:2048
	v_lshl_add_u64 v[72:73], v[110:111], 0, s[70:71]
	v_add_co_u32_e32 v72, vcc, s3, v72
	s_nop 1
	v_addc_co_u32_e32 v73, vcc, 0, v73, vcc
	global_load_dwordx4 v[74:77], v[72:73], off offset:2048
	v_lshl_add_u64 v[206:207], v[114:115], 0, s[70:71]
	v_add_co_u32_e32 v78, vcc, s3, v206
	s_nop 1
	v_addc_co_u32_e32 v79, vcc, 0, v207, vcc
	global_load_dwordx4 v[80:83], v[78:79], off offset:2048
	v_lshl_add_u64 v[214:215], v[118:119], 0, s[70:71]
	v_add_co_u32_e32 v84, vcc, s3, v214
	s_nop 1
	v_addc_co_u32_e32 v85, vcc, 0, v215, vcc
	global_load_dwordx4 v[86:89], v[84:85], off offset:2048
	v_add_u32_e32 v126, s19, v124
	v_mad_i64_i32 v[128:129], s[100:101], v126, s0, v[36:37]
	v_lshl_add_u64 v[130:131], v[128:129], 0, s[70:71]
	v_add_co_u32_e32 v130, vcc, s23, v130
	s_nop 1
	v_addc_co_u32_e32 v131, vcc, 0, v131, vcc
	global_load_dwordx4 v[132:135], v[130:131], off
	global_load_dwordx4 v[136:139], v196, s[86:87]
	global_load_dwordx4 v[246:249], v197, s[86:87] offset:2048
	s_nop 0
	s_nop 0
	s_nop 1
	s_nop 0
	s_nop 0
	s_nop 0
	s_nop 0
	s_nop 1
	s_nop 0
	s_nop 0
	s_nop 0
	s_nop 1
	s_nop 0
	s_nop 0
	s_nop 0
	s_nop 0
	s_nop 0
	s_nop 0
	s_nop 0
	s_nop 0
	s_waitcnt vmcnt(15)
	v_cndmask_b32_e64 v8, 0, v3, s[36:37]
	v_cndmask_b32_e64 v9, 0, v2, s[36:37]
	s_nop 0
	s_nop 0
	v_cndmask_b32_e64 v6, 0, v5, s[36:37]
	s_nop 0
	s_nop 0
	v_cndmask_b32_e64 v7, 0, v4, s[36:37]
	s_nop 0
	v_and_b32_e32 v13, 0xffff0000, v9
	v_lshlrev_b32_e32 v12, 16, v9
	v_and_b32_e32 v47, 0xffff0000, v8
	v_lshlrev_b32_e32 v46, 16, v8
	v_and_b32_e32 v43, 0xffff0000, v7
	v_lshlrev_b32_e32 v42, 16, v7
	v_and_b32_e32 v39, 0xffff0000, v6
	v_lshlrev_b32_e32 v38, 16, v6
	s_add_u32 s36, s86, 0x2000
	s_addc_u32 s37, s87, 0
	s_waitcnt vmcnt(14)
	v_cndmask_b32_e64 v14, 0, v209, s[38:39]
	v_cndmask_b32_e64 v15, 0, v208, s[38:39]
	s_nop 0
	s_nop 0
	v_cndmask_b32_e64 v10, 0, v211, s[38:39]
	s_nop 0
	s_nop 0
	v_cndmask_b32_e64 v11, 0, v210, s[38:39]
	s_nop 0
	s_nop 0
	v_and_b32_e32 v45, 0xffff0000, v11
	s_nop 0
	s_nop 0
	v_lshlrev_b32_e32 v44, 16, v11
	v_and_b32_e32 v41, 0xffff0000, v10
	v_lshlrev_b32_e32 v40, 16, v10
	v_and_b32_e32 v17, 0xffff0000, v15
	v_lshlrev_b32_e32 v16, 16, v15
	v_and_b32_e32 v49, 0xffff0000, v14
	v_lshlrev_b32_e32 v48, 16, v14
	s_add_u32 s38, s86, 0x3800
	s_addc_u32 s39, s87, 0
	s_waitcnt vmcnt(13)
	v_cndmask_b32_e64 v50, 0, v219, s[40:41]
	v_cndmask_b32_e64 v51, 0, v218, s[40:41]
	v_cndmask_b32_e64 v52, 0, v217, s[40:41]
	v_cndmask_b32_e64 v30, 0, v216, s[40:41]
	s_nop 0
	s_nop 0
	s_nop 0
	s_nop 0
	s_nop 0
	s_nop 0
	s_waitcnt vmcnt(9)
	v_pk_fma_f32 v[4:5], v[228:229], v[42:43], v[224:225]
	s_waitcnt vmcnt(8)
	v_pk_fma_f32 v[18:19], v[22:23], v[12:13], v[18:19]
	global_load_dwordx4 v[12:15], v161, s[36:37] offset:16
	s_nop 0
	v_and_b32_e32 v53, 0xffff0000, v220
	v_lshlrev_b32_e32 v0, 16, v220
	v_pk_fma_f32 v[20:21], v[24:25], v[46:47], v[20:21]
	v_and_b32_e32 v25, 0xffff0000, v52
	v_lshlrev_b32_e32 v24, 16, v52
	v_and_b32_e32 v9, 0xffff0000, v51
	v_lshlrev_b32_e32 v8, 16, v51
	v_pk_fma_f32 v[6:7], v[230:231], v[38:39], v[226:227]
	v_and_b32_e32 v10, 0xffff0000, v223
	v_lshlrev_b32_e32 v11, 16, v223
	s_waitcnt vmcnt(0)
	v_pk_fma_f32 v[4:5], v[12:13], v[44:45], v[4:5]
	v_pk_fma_f32 v[22:23], v[26:27], v[16:17], v[18:19]
	v_and_b32_e32 v27, 0xffff0000, v30
	v_lshlrev_b32_e32 v26, 16, v30
	global_load_dwordx4 v[16:19], v161, s[38:39] offset:16
	s_nop 0
	v_pk_fma_f32 v[20:21], v[28:29], v[48:49], v[20:21]
	v_pk_fma_f32 v[6:7], v[14:15], v[40:41], v[6:7]
	s_waitcnt vmcnt(0)
	v_pk_fma_f32 v[4:5], v[16:17], v[8:9], v[4:5]
	v_pk_fma_f32 v[22:23], v[232:233], v[26:27], v[22:23]
	ds_read_u16 v27, v101 offset:512
	ds_read_u16 v30, v101 offset:3584
	v_mul_f32_e32 v26, 0xbfb8aa3b, v0
	v_exp_f32_e32 v26, v26
	v_pk_fma_f32 v[20:21], v[234:235], v[24:25], v[20:21]
	v_and_b32_e32 v16, 0xffff0000, v222
	s_waitcnt lgkmcnt(0)
	v_lshlrev_b32_e32 v31, 16, v30
	v_lshlrev_b32_e32 v30, 16, v27
	v_mul_f32_e32 v27, 0xbfb8aa3b, v53
	v_exp_f32_e32 v27, v27
	v_pk_mul_f32 v[22:23], v[22:23], v[30:31]
	v_lshlrev_b32_e32 v2, 16, v222
	v_mul_f32_e32 v8, 0xbfb8aa3b, v2
	v_pk_add_f32 v[26:27], v[26:27], 1.0 op_sel_hi:[1,0]
	v_exp_f32_e32 v8, v8
	v_div_scale_f32 v30, s[20:21], v27, v27, v53
	v_rcp_f32_e32 v31, v30
	s_nop 0
	v_fma_f32 v54, -v30, v31, 1.0
	v_fmac_f32_e32 v31, v54, v31
	v_div_scale_f32 v54, vcc, v53, v27, v53
	v_mul_f32_e32 v55, v54, v31
	v_fma_f32 v56, -v30, v55, v54
	v_fmac_f32_e32 v55, v56, v31
	v_fma_f32 v30, -v30, v55, v54
	v_div_fmas_f32 v30, v30, v31, v55
	v_div_fixup_f32 v27, v30, v27, v53
	v_div_scale_f32 v30, s[20:21], v26, v26, v0
	v_rcp_f32_e32 v31, v30
	s_nop 0
	v_fma_f32 v53, -v30, v31, 1.0
	v_fmac_f32_e32 v31, v53, v31
	v_div_scale_f32 v53, vcc, v0, v26, v0
	v_mul_f32_e32 v54, v53, v31
	v_fma_f32 v55, -v30, v54, v53
	v_fmac_f32_e32 v54, v55, v31
	v_fma_f32 v30, -v30, v54, v53
	v_div_fmas_f32 v30, v30, v31, v54
	v_div_fixup_f32 v26, v30, v26, v0
	v_pk_mul_f32 v[22:23], v[26:27], v[22:23]
	v_and_b32_e32 v26, 0xffff0000, v221
	v_lshlrev_b32_e32 v27, 16, v221
	ds_read_u16 v1, v101 offset:6656
	ds_read_u16 v24, v101 offset:9728
	v_mul_f32_e32 v0, 0xbfb8aa3b, v27
	v_exp_f32_e32 v0, v0
	ds_read_u16 v9, v101 offset:12800
	ds_read_u16 v12, v101 offset:15872
	s_waitcnt lgkmcnt(2)
	v_lshlrev_b32_e32 v25, 16, v24
	v_lshlrev_b32_e32 v24, 16, v1
	v_mul_f32_e32 v1, 0xbfb8aa3b, v26
	v_exp_f32_e32 v1, v1
	v_pk_mul_f32 v[20:21], v[20:21], v[24:25]
	s_waitcnt lgkmcnt(0)
	v_lshlrev_b32_e32 v13, 16, v12
	v_lshlrev_b32_e32 v12, 16, v9
	v_pk_add_f32 v[0:1], v[0:1], 1.0 op_sel_hi:[1,0]
	v_mul_f32_e32 v9, 0xbfb8aa3b, v16
	v_div_scale_f32 v24, s[20:21], v1, v1, v26
	v_rcp_f32_e32 v25, v24
	v_exp_f32_e32 v9, v9
	v_pk_mul_f32 v[4:5], v[4:5], v[12:13]
	v_fma_f32 v28, -v24, v25, 1.0
	v_fmac_f32_e32 v25, v28, v25
	v_div_scale_f32 v28, vcc, v26, v1, v26
	v_mul_f32_e32 v29, v28, v25
	v_fma_f32 v30, -v24, v29, v28
	v_fmac_f32_e32 v29, v30, v25
	v_fma_f32 v24, -v24, v29, v28
	v_div_fmas_f32 v24, v24, v25, v29
	v_div_fixup_f32 v1, v24, v1, v26
	v_div_scale_f32 v24, s[20:21], v0, v0, v27
	v_rcp_f32_e32 v25, v24
	v_pk_add_f32 v[8:9], v[8:9], 1.0 op_sel_hi:[1,0]
	v_fma_f32 v26, -v24, v25, 1.0
	v_fmac_f32_e32 v25, v26, v25
	v_div_scale_f32 v26, vcc, v27, v0, v27
	v_div_scale_f32 v12, s[20:21], v9, v9, v16
	v_mul_f32_e32 v28, v26, v25
	v_rcp_f32_e32 v13, v12
	v_fma_f32 v29, -v24, v28, v26
	v_fmac_f32_e32 v28, v29, v25
	v_fma_f32 v24, -v24, v28, v26
	v_div_fmas_f32 v24, v24, v25, v28
	v_fma_f32 v17, -v12, v13, 1.0
	v_div_fixup_f32 v0, v24, v0, v27
	v_fmac_f32_e32 v13, v17, v13
	v_div_scale_f32 v17, vcc, v16, v9, v16
	v_pk_mul_f32 v[0:1], v[0:1], v[20:21]
	v_mul_f32_e32 v20, v17, v13
	v_fma_f32 v21, -v12, v20, v17
	v_fmac_f32_e32 v20, v21, v13
	v_fma_f32 v12, -v12, v20, v17
	v_div_fmas_f32 v12, v12, v13, v20
	v_div_fixup_f32 v9, v12, v9, v16
	v_div_scale_f32 v12, s[20:21], v8, v8, v2
	v_rcp_f32_e32 v13, v12
	s_nop 0
	v_fma_f32 v16, -v12, v13, 1.0
	v_fmac_f32_e32 v13, v16, v13
	v_div_scale_f32 v16, vcc, v2, v8, v2
	v_mul_f32_e32 v17, v16, v13
	v_fma_f32 v20, -v12, v17, v16
	v_fmac_f32_e32 v17, v20, v13
	v_fma_f32 v12, -v12, v17, v16
	v_div_fmas_f32 v12, v12, v13, v17
	v_div_fixup_f32 v8, v12, v8, v2
	v_pk_mul_f32 v[4:5], v[8:9], v[4:5]
	v_and_b32_e32 v9, 0xffff0000, v50
	v_lshlrev_b32_e32 v8, 16, v50
	v_pk_fma_f32 v[6:7], v[18:19], v[8:9], v[6:7]
	ds_read_u16 v3, v101 offset:18944
	ds_read_u16 v8, v101 offset:22016
	v_mul_f32_e32 v2, 0xbfb8aa3b, v11
	v_exp_f32_e32 v2, v2
	s_waitcnt lgkmcnt(0)
	v_lshlrev_b32_e32 v9, 16, v8
	v_lshlrev_b32_e32 v8, 16, v3
	v_mul_f32_e32 v3, 0xbfb8aa3b, v10
	v_exp_f32_e32 v3, v3
	v_pk_mul_f32 v[6:7], v[6:7], v[8:9]
	v_pk_add_f32 v[2:3], v[2:3], 1.0 op_sel_hi:[1,0]
	s_nop 0
	v_div_scale_f32 v8, s[20:21], v3, v3, v10
	v_rcp_f32_e32 v9, v8
	s_nop 0
	v_fma_f32 v12, -v8, v9, 1.0
	v_fmac_f32_e32 v9, v12, v9
	v_div_scale_f32 v12, vcc, v10, v3, v10
	v_mul_f32_e32 v13, v12, v9
	v_fma_f32 v14, -v8, v13, v12
	v_fmac_f32_e32 v13, v14, v9
	v_fma_f32 v8, -v8, v13, v12
	v_div_fmas_f32 v8, v8, v9, v13
	v_div_fixup_f32 v3, v8, v3, v10
	v_div_scale_f32 v8, s[20:21], v2, v2, v11
	v_rcp_f32_e32 v9, v8
	s_nop 0
	v_fma_f32 v10, -v8, v9, 1.0
	v_fmac_f32_e32 v9, v10, v9
	v_div_scale_f32 v10, vcc, v11, v2, v11
	v_mul_f32_e32 v12, v10, v9
	v_fma_f32 v13, -v8, v12, v10
	v_fmac_f32_e32 v12, v13, v9
	v_fma_f32 v8, -v8, v12, v10
	v_div_fmas_f32 v8, v8, v9, v12
	v_div_fixup_f32 v2, v8, v2, v11
	v_pk_mul_f32 v[2:3], v[2:3], v[6:7]
	v_cvt_pk_bf16_f32 v4, v4, v5
	v_cvt_pk_bf16_f32 v2, v2, v3
	v_mov_b32_e32 v3, v2
	v_mov_b32_e32 v2, v4
	v_lshlrev_b64 v[4:5], 12, v[34:35]
	v_lshl_add_u64 v[4:5], s[30:31], 0, v[4:5]
	v_bfe_u32 v12, v23, 16, 1
	v_bfe_u32 v13, v22, 16, 1
	v_lshl_add_u64 v[4:5], v[4:5], 0, s[70:71]
	v_add3_u32 v13, v22, v13, s94
	v_add3_u32 v12, v23, v12, s94
	v_cvt_pk_bf16_f32 v0, v0, v1
	v_add_co_u32_e32 v4, vcc, s22, v4
	v_mov_b32_e32 v1, v0
	v_perm_b32 v0, v12, v13, s95
	v_addc_co_u32_e32 v5, vcc, 0, v5, vcc
	global_store_dwordx4 v[4:5], v[0:3], off offset:3072
	v_mov_b32_e32 v32, v234
	v_mov_b32_e32 v33, v235
	v_add_u32_e32 v34, s19, v124
	v_ashrrev_i32_e32 v35, 31, v34
	s_nop 0
	s_nop 0
	s_nop 1
	s_nop 0
	s_nop 0
	s_nop 0
	s_nop 0
	s_nop 1
	s_nop 0
	s_nop 0
	s_nop 0
	s_nop 0
	s_nop 1
	s_nop 0
	s_nop 0
	s_nop 0
	s_nop 0
	s_nop 0
	s_nop 1
	s_nop 0
	s_nop 0
	global_load_dwordx4 v[230:233], v161, s[84:85] offset:2064
	global_load_dwordx4 v[18:21], v161, s[84:85] offset:2048
	global_load_dwordx4 v[234:237], v161, s[86:87] offset:2064
	global_load_dwordx4 v[22:25], v161, s[86:87] offset:2048
	global_load_dwordx4 v[238:241], v161, s[36:37] offset:16
	s_nop 0
	global_load_dwordx4 v[242:245], v161, s[38:39] offset:16
	s_nop 0
	v_mov_b32_e32 v0, v74
	v_mov_b32_e32 v1, v75
	v_mov_b32_e32 v2, v76
	v_mov_b32_e32 v3, v77
	v_mov_b32_e32 v26, v136
	v_mov_b32_e32 v27, v137
	v_mov_b32_e32 v28, v138
	v_mov_b32_e32 v29, v139
	v_mov_b32_e32 v208, v80
	v_mov_b32_e32 v209, v81
	v_mov_b32_e32 v210, v82
	v_mov_b32_e32 v211, v83
	v_mov_b32_e32 v216, v86
	v_mov_b32_e32 v217, v87
	v_mov_b32_e32 v218, v88
	v_mov_b32_e32 v219, v89
	v_mov_b32_e32 v226, v132
	v_mov_b32_e32 v227, v133
	v_mov_b32_e32 v228, v134
	v_mov_b32_e32 v229, v135
	s_waitcnt vmcnt(11)
	v_cndmask_b32_e64 v6, 0, v1, s[50:51]
	v_cndmask_b32_e64 v7, 0, v0, s[50:51]
	s_nop 0
	s_nop 0
	v_cndmask_b32_e64 v4, 0, v3, s[50:51]
	s_nop 0
	s_nop 0
	v_cndmask_b32_e64 v5, 0, v2, s[50:51]
	s_nop 0
	v_and_b32_e32 v13, 0xffff0000, v7
	v_lshlrev_b32_e32 v12, 16, v7
	v_and_b32_e32 v47, 0xffff0000, v6
	v_lshlrev_b32_e32 v46, 16, v6
	v_and_b32_e32 v43, 0xffff0000, v5
	v_lshlrev_b32_e32 v42, 16, v5
	v_and_b32_e32 v39, 0xffff0000, v4
	v_lshlrev_b32_e32 v38, 16, v4
	s_waitcnt vmcnt(10)
	v_cndmask_b32_e64 v10, 0, v209, s[56:57]
	v_cndmask_b32_e64 v11, 0, v208, s[56:57]
	s_nop 0
	s_nop 0
	v_cndmask_b32_e64 v8, 0, v211, s[56:57]
	s_nop 0
	s_nop 0
	v_cndmask_b32_e64 v9, 0, v210, s[56:57]
	s_nop 0
	v_and_b32_e32 v17, 0xffff0000, v11
	v_lshlrev_b32_e32 v16, 16, v11
	v_and_b32_e32 v49, 0xffff0000, v10
	v_lshlrev_b32_e32 v48, 16, v10
	v_and_b32_e32 v45, 0xffff0000, v9
	v_lshlrev_b32_e32 v44, 16, v9
	v_and_b32_e32 v41, 0xffff0000, v8
	v_lshlrev_b32_e32 v40, 16, v8
	s_waitcnt vmcnt(9)
	v_cndmask_b32_e64 v52, 0, v217, s[60:61]
	v_cndmask_b32_e64 v30, 0, v216, s[60:61]
	s_nop 0
	s_nop 0
	s_nop 0
	v_cndmask_b32_e64 v50, 0, v219, s[60:61]
	s_nop 0
	s_nop 0
	v_cndmask_b32_e64 v51, 0, v218, s[60:61]
	s_nop 0
	s_nop 0
	s_nop 0
	s_nop 0
	s_nop 0
	s_nop 0
	s_waitcnt vmcnt(5)
	v_pk_fma_f32 v[4:5], v[234:235], v[42:43], v[230:231]
	s_waitcnt vmcnt(4)
	v_pk_fma_f32 v[18:19], v[22:23], v[12:13], v[18:19]
	s_nop 0
	s_nop 0
	v_pk_fma_f32 v[20:21], v[24:25], v[46:47], v[20:21]
	v_and_b32_e32 v25, 0xffff0000, v52
	v_lshlrev_b32_e32 v24, 16, v52
	v_and_b32_e32 v9, 0xffff0000, v51
	v_lshlrev_b32_e32 v8, 16, v51
	v_pk_fma_f32 v[6:7], v[236:237], v[38:39], v[232:233]
	v_and_b32_e32 v10, 0xffff0000, v229
	v_lshlrev_b32_e32 v11, 16, v229
	s_waitcnt vmcnt(3)
	v_pk_fma_f32 v[4:5], v[238:239], v[44:45], v[4:5]
	s_waitcnt vmcnt(2)
	v_pk_fma_f32 v[22:23], v[26:27], v[16:17], v[18:19]
	v_and_b32_e32 v27, 0xffff0000, v30
	v_lshlrev_b32_e32 v26, 16, v30
	s_nop 0
	s_nop 0
	v_pk_fma_f32 v[20:21], v[28:29], v[48:49], v[20:21]
	v_pk_fma_f32 v[6:7], v[240:241], v[40:41], v[6:7]
	s_waitcnt vmcnt(1)
	v_pk_fma_f32 v[4:5], v[242:243], v[8:9], v[4:5]
	s_waitcnt vmcnt(0)
	s_waitcnt vmcnt(0)
	v_lshl_add_u64 v[66:67], v[108:109], 0, s[70:71]
	v_add_co_u32_e32 v66, vcc, s3, v66
	s_nop 1
	v_addc_co_u32_e32 v67, vcc, 0, v67, vcc
	global_load_dwordx4 v[68:71], v[66:67], off offset:2048
	v_lshl_add_u64 v[206:207], v[112:113], 0, s[70:71]
	v_add_co_u32_e32 v72, vcc, s3, v206
	s_nop 1
	v_addc_co_u32_e32 v73, vcc, 0, v207, vcc
	global_load_dwordx4 v[208:211], v[72:73], off offset:2048
	v_lshl_add_u64 v[214:215], v[116:117], 0, s[70:71]
	v_add_co_u32_e32 v74, vcc, s3, v214
	s_nop 1
	v_addc_co_u32_e32 v75, vcc, 0, v215, vcc
	global_load_dwordx4 v[216:219], v[74:75], off offset:2048
	v_add_u32_e32 v78, s19, v123
	v_mad_i64_i32 v[222:223], s[100:101], v78, s0, v[36:37]
	v_lshl_add_u64 v[224:225], v[222:223], 0, s[70:71]
	v_add_co_u32_e32 v76, vcc, s23, v224
	s_nop 1
	v_addc_co_u32_e32 v77, vcc, 0, v225, vcc
	global_load_dwordx4 v[80:83], v[76:77], off
	global_load_dwordx4 v[230:233], v161, s[84:85] offset:2064
	global_load_dwordx4 v[84:87], v161, s[84:85] offset:2048
	global_load_dwordx4 v[234:237], v161, s[86:87] offset:2064
	global_load_dwordx4 v[88:91], v161, s[86:87] offset:2048
	global_load_dwordx4 v[126:129], v161, s[36:37] offset:16
	global_load_dwordx4 v[130:133], v196, s[86:87]
	global_load_dwordx4 v[134:137], v161, s[38:39] offset:16
	global_load_dwordx4 v[138:141], v197, s[86:87] offset:2048
	v_pk_fma_f32 v[22:23], v[246:247], v[26:27], v[22:23]
	ds_read_u16 v27, v101 offset:1024
	ds_read_u16 v31, v101 offset:4096
	v_and_b32_e32 v30, 0xffff0000, v226
	v_lshlrev_b32_e32 v0, 16, v226
	v_mul_f32_e32 v26, 0xbfb8aa3b, v0
	s_waitcnt lgkmcnt(1)
	v_lshlrev_b32_e32 v54, 16, v27
	v_mul_f32_e32 v27, 0xbfb8aa3b, v30
	v_exp_f32_e32 v26, v26
	v_exp_f32_e32 v27, v27
	s_waitcnt lgkmcnt(0)
	v_lshlrev_b32_e32 v55, 16, v31
	v_pk_mul_f32 v[22:23], v[22:23], v[54:55]
	v_pk_fma_f32 v[20:21], v[248:249], v[24:25], v[20:21]
	v_pk_add_f32 v[26:27], v[26:27], 1.0 op_sel_hi:[1,0]
	v_and_b32_e32 v16, 0xffff0000, v228
	v_div_scale_f32 v31, s[20:21], v27, v27, v30
	v_rcp_f32_e32 v53, v31
	v_lshlrev_b32_e32 v2, 16, v228
	v_mul_f32_e32 v8, 0xbfb8aa3b, v2
	v_exp_f32_e32 v8, v8
	v_fma_f32 v54, -v31, v53, 1.0
	v_fmac_f32_e32 v53, v54, v53
	v_div_scale_f32 v54, vcc, v30, v27, v30
	v_mul_f32_e32 v55, v54, v53
	v_fma_f32 v56, -v31, v55, v54
	v_fmac_f32_e32 v55, v56, v53
	v_fma_f32 v31, -v31, v55, v54
	v_div_fmas_f32 v31, v31, v53, v55
	v_div_fixup_f32 v27, v31, v27, v30
	v_div_scale_f32 v30, s[20:21], v26, v26, v0
	v_rcp_f32_e32 v31, v30
	s_nop 0
	v_fma_f32 v53, -v30, v31, 1.0
	v_fmac_f32_e32 v31, v53, v31
	v_div_scale_f32 v53, vcc, v0, v26, v0
	v_mul_f32_e32 v54, v53, v31
	v_fma_f32 v55, -v30, v54, v53
	v_fmac_f32_e32 v54, v55, v31
	v_fma_f32 v30, -v30, v54, v53
	v_div_fmas_f32 v30, v30, v31, v54
	v_div_fixup_f32 v26, v30, v26, v0
	v_pk_mul_f32 v[22:23], v[26:27], v[22:23]
	v_and_b32_e32 v26, 0xffff0000, v227
	v_lshlrev_b32_e32 v27, 16, v227
	ds_read_u16 v1, v101 offset:7168
	ds_read_u16 v24, v101 offset:10240
	v_mul_f32_e32 v0, 0xbfb8aa3b, v27
	v_exp_f32_e32 v0, v0
	ds_read_u16 v9, v101 offset:13312
	ds_read_u16 v12, v101 offset:16384
	s_waitcnt lgkmcnt(2)
	v_lshlrev_b32_e32 v25, 16, v24
	v_lshlrev_b32_e32 v24, 16, v1
	v_mul_f32_e32 v1, 0xbfb8aa3b, v26
	v_exp_f32_e32 v1, v1
	v_pk_mul_f32 v[20:21], v[20:21], v[24:25]
	s_waitcnt lgkmcnt(0)
	v_lshlrev_b32_e32 v13, 16, v12
	v_lshlrev_b32_e32 v12, 16, v9
	v_pk_add_f32 v[0:1], v[0:1], 1.0 op_sel_hi:[1,0]
	v_mul_f32_e32 v9, 0xbfb8aa3b, v16
	v_div_scale_f32 v24, s[20:21], v1, v1, v26
	v_rcp_f32_e32 v25, v24
	v_exp_f32_e32 v9, v9
	v_pk_mul_f32 v[4:5], v[4:5], v[12:13]
	v_fma_f32 v28, -v24, v25, 1.0
	v_fmac_f32_e32 v25, v28, v25
	v_div_scale_f32 v28, vcc, v26, v1, v26
	v_mul_f32_e32 v29, v28, v25
	v_fma_f32 v30, -v24, v29, v28
	v_fmac_f32_e32 v29, v30, v25
	v_fma_f32 v24, -v24, v29, v28
	v_div_fmas_f32 v24, v24, v25, v29
	v_div_fixup_f32 v1, v24, v1, v26
	v_div_scale_f32 v24, s[20:21], v0, v0, v27
	v_rcp_f32_e32 v25, v24
	v_pk_add_f32 v[8:9], v[8:9], 1.0 op_sel_hi:[1,0]
	v_fma_f32 v26, -v24, v25, 1.0
	v_fmac_f32_e32 v25, v26, v25
	v_div_scale_f32 v26, vcc, v27, v0, v27
	v_div_scale_f32 v12, s[20:21], v9, v9, v16
	v_mul_f32_e32 v28, v26, v25
	v_rcp_f32_e32 v13, v12
	v_fma_f32 v29, -v24, v28, v26
	v_fmac_f32_e32 v28, v29, v25
	v_fma_f32 v24, -v24, v28, v26
	v_div_fmas_f32 v24, v24, v25, v28
	v_fma_f32 v17, -v12, v13, 1.0
	v_div_fixup_f32 v0, v24, v0, v27
	v_fmac_f32_e32 v13, v17, v13
	v_div_scale_f32 v17, vcc, v16, v9, v16
	v_pk_mul_f32 v[0:1], v[0:1], v[20:21]
	v_mul_f32_e32 v20, v17, v13
	v_fma_f32 v21, -v12, v20, v17
	v_fmac_f32_e32 v20, v21, v13
	v_fma_f32 v12, -v12, v20, v17
	v_div_fmas_f32 v12, v12, v13, v20
	v_div_fixup_f32 v9, v12, v9, v16
	v_div_scale_f32 v12, s[20:21], v8, v8, v2
	v_rcp_f32_e32 v13, v12
	s_nop 0
	v_fma_f32 v16, -v12, v13, 1.0
	v_fmac_f32_e32 v13, v16, v13
	v_div_scale_f32 v16, vcc, v2, v8, v2
	v_mul_f32_e32 v17, v16, v13
	v_fma_f32 v20, -v12, v17, v16
	v_fmac_f32_e32 v17, v20, v13
	v_fma_f32 v12, -v12, v17, v16
	v_div_fmas_f32 v12, v12, v13, v17
	v_div_fixup_f32 v8, v12, v8, v2
	v_pk_mul_f32 v[4:5], v[8:9], v[4:5]
	v_and_b32_e32 v9, 0xffff0000, v50
	v_lshlrev_b32_e32 v8, 16, v50
	v_pk_fma_f32 v[6:7], v[244:245], v[8:9], v[6:7]
	ds_read_u16 v3, v101 offset:19456
	ds_read_u16 v8, v101 offset:22528
	v_mul_f32_e32 v2, 0xbfb8aa3b, v11
	v_exp_f32_e32 v2, v2
	s_waitcnt lgkmcnt(0)
	v_lshlrev_b32_e32 v9, 16, v8
	v_lshlrev_b32_e32 v8, 16, v3
	v_mul_f32_e32 v3, 0xbfb8aa3b, v10
	v_exp_f32_e32 v3, v3
	v_pk_mul_f32 v[6:7], v[6:7], v[8:9]
	v_pk_add_f32 v[2:3], v[2:3], 1.0 op_sel_hi:[1,0]
	s_nop 0
	v_div_scale_f32 v8, s[20:21], v3, v3, v10
	v_rcp_f32_e32 v9, v8
	s_nop 0
	v_fma_f32 v12, -v8, v9, 1.0
	v_fmac_f32_e32 v9, v12, v9
	v_div_scale_f32 v12, vcc, v10, v3, v10
	v_mul_f32_e32 v13, v12, v9
	v_fma_f32 v14, -v8, v13, v12
	v_fmac_f32_e32 v13, v14, v9
	v_fma_f32 v8, -v8, v13, v12
	v_div_fmas_f32 v8, v8, v9, v13
	v_div_fixup_f32 v3, v8, v3, v10
	v_div_scale_f32 v8, s[20:21], v2, v2, v11
	v_rcp_f32_e32 v9, v8
	s_nop 0
	v_fma_f32 v10, -v8, v9, 1.0
	v_fmac_f32_e32 v9, v10, v9
	v_div_scale_f32 v10, vcc, v11, v2, v11
	v_mul_f32_e32 v12, v10, v9
	v_fma_f32 v13, -v8, v12, v10
	v_fmac_f32_e32 v12, v13, v9
	v_fma_f32 v8, -v8, v12, v10
	v_div_fmas_f32 v8, v8, v9, v12
	v_div_fixup_f32 v2, v8, v2, v11
	v_pk_mul_f32 v[2:3], v[2:3], v[6:7]
	v_cvt_pk_bf16_f32 v4, v4, v5
	v_cvt_pk_bf16_f32 v2, v2, v3
	v_mov_b32_e32 v3, v2
	v_mov_b32_e32 v2, v4
	v_lshlrev_b64 v[4:5], 12, v[34:35]
	v_lshl_add_u64 v[4:5], s[30:31], 0, v[4:5]
	v_bfe_u32 v12, v23, 16, 1
	v_bfe_u32 v13, v22, 16, 1
	v_lshl_add_u64 v[4:5], v[4:5], 0, s[70:71]
	v_add3_u32 v13, v22, v13, s94
	v_add3_u32 v12, v23, v12, s94
	v_cvt_pk_bf16_f32 v0, v0, v1
	v_add_co_u32_e32 v4, vcc, s22, v4
	v_mov_b32_e32 v1, v0
	v_perm_b32 v0, v12, v13, s95
	v_addc_co_u32_e32 v5, vcc, 0, v5, vcc
	global_store_dwordx4 v[4:5], v[0:3], off offset:3072
	v_mov_b32_e32 v15, v241
	v_mov_b32_e32 v18, v244
	v_mov_b32_e32 v19, v245
	v_mov_b32_e32 v32, v248
	v_mov_b32_e32 v33, v249
	v_add_u32_e32 v34, s19, v123
	v_ashrrev_i32_e32 v35, 31, v34
	s_nop 0
	s_nop 0
	s_nop 1
	s_nop 0
	s_nop 0
	s_nop 0
	s_nop 0
	s_nop 1
	s_nop 0
	s_nop 0
	s_nop 0
	s_nop 0
	s_nop 1
	s_nop 0
	s_nop 0
	s_nop 0
	s_nop 0
	s_nop 0
	s_nop 1
	s_nop 0
	s_nop 0
	s_nop 0
	s_nop 0
	s_nop 0
	s_nop 0
	s_nop 0
	s_nop 0
	s_nop 0
	s_nop 0
	s_waitcnt vmcnt(12)
	v_mov_b32_e32 v0, v68
	v_mov_b32_e32 v1, v69
	v_mov_b32_e32 v2, v70
	v_mov_b32_e32 v3, v71
	s_waitcnt vmcnt(7)
	v_mov_b32_e32 v18, v84
	v_mov_b32_e32 v19, v85
	v_mov_b32_e32 v20, v86
	v_mov_b32_e32 v21, v87
	s_waitcnt vmcnt(5)
	v_mov_b32_e32 v22, v88
	v_mov_b32_e32 v23, v89
	v_mov_b32_e32 v24, v90
	v_mov_b32_e32 v25, v91
	s_waitcnt vmcnt(3)
	v_mov_b32_e32 v26, v130
	v_mov_b32_e32 v27, v131
	v_mov_b32_e32 v28, v132
	v_mov_b32_e32 v29, v133
	v_mov_b32_e32 v226, v80
	v_mov_b32_e32 v227, v81
	v_mov_b32_e32 v228, v82
	v_mov_b32_e32 v229, v83
	v_mov_b32_e32 v238, v126
	v_mov_b32_e32 v239, v127
	v_mov_b32_e32 v240, v128
	v_mov_b32_e32 v241, v129
	s_waitcnt vmcnt(2)
	v_mov_b32_e32 v242, v134
	v_mov_b32_e32 v243, v135
	v_mov_b32_e32 v244, v136
	v_mov_b32_e32 v245, v137
	s_waitcnt vmcnt(1)
	v_mov_b32_e32 v246, v138
	v_mov_b32_e32 v247, v139
	v_mov_b32_e32 v248, v140
	v_mov_b32_e32 v249, v141
	s_waitcnt vmcnt(11)
	v_cndmask_b32_e64 v6, 0, v1, s[48:49]
	v_cndmask_b32_e64 v7, 0, v0, s[48:49]
	s_nop 0
	s_nop 0
	v_cndmask_b32_e64 v4, 0, v3, s[48:49]
	s_nop 0
	s_nop 0
	v_cndmask_b32_e64 v5, 0, v2, s[48:49]
	s_nop 0
	v_and_b32_e32 v13, 0xffff0000, v7
	v_lshlrev_b32_e32 v12, 16, v7
	v_and_b32_e32 v47, 0xffff0000, v6
	v_lshlrev_b32_e32 v46, 16, v6
	v_and_b32_e32 v43, 0xffff0000, v5
	v_lshlrev_b32_e32 v42, 16, v5
	v_and_b32_e32 v39, 0xffff0000, v4
	v_lshlrev_b32_e32 v38, 16, v4
	s_waitcnt vmcnt(10)
	v_cndmask_b32_e64 v10, 0, v209, s[54:55]
	v_cndmask_b32_e64 v11, 0, v208, s[54:55]
	s_nop 0
	s_nop 0
	v_cndmask_b32_e64 v8, 0, v211, s[54:55]
	s_nop 0
	s_nop 0
	v_cndmask_b32_e64 v9, 0, v210, s[54:55]
	s_nop 0
	v_and_b32_e32 v17, 0xffff0000, v11
	v_lshlrev_b32_e32 v16, 16, v11
	v_and_b32_e32 v49, 0xffff0000, v10
	v_lshlrev_b32_e32 v48, 16, v10
	v_and_b32_e32 v45, 0xffff0000, v9
	v_lshlrev_b32_e32 v44, 16, v9
	v_and_b32_e32 v41, 0xffff0000, v8
	v_lshlrev_b32_e32 v40, 16, v8
	s_waitcnt vmcnt(9)
	v_cndmask_b32_e64 v52, 0, v217, s[58:59]
	v_cndmask_b32_e64 v30, 0, v216, s[58:59]
	s_nop 0
	s_nop 0
	s_nop 0
	v_cndmask_b32_e64 v50, 0, v219, s[58:59]
	s_nop 0
	s_nop 0
	v_cndmask_b32_e64 v51, 0, v218, s[58:59]
	s_nop 0
	s_nop 0
	s_nop 0
	s_nop 0
	s_nop 0
	s_nop 0
	s_waitcnt vmcnt(5)
	v_pk_fma_f32 v[4:5], v[234:235], v[42:43], v[230:231]
	s_waitcnt vmcnt(4)
	v_pk_fma_f32 v[18:19], v[22:23], v[12:13], v[18:19]
	s_nop 0
	s_nop 0
	v_pk_fma_f32 v[20:21], v[24:25], v[46:47], v[20:21]
	v_and_b32_e32 v25, 0xffff0000, v52
	v_lshlrev_b32_e32 v24, 16, v52
	v_and_b32_e32 v9, 0xffff0000, v51
	v_lshlrev_b32_e32 v8, 16, v51
	v_pk_fma_f32 v[6:7], v[236:237], v[38:39], v[232:233]
	v_and_b32_e32 v10, 0xffff0000, v229
	v_lshlrev_b32_e32 v11, 16, v229
	s_waitcnt vmcnt(3)
	v_pk_fma_f32 v[4:5], v[238:239], v[44:45], v[4:5]
	s_waitcnt vmcnt(2)
	v_pk_fma_f32 v[22:23], v[26:27], v[16:17], v[18:19]
	v_and_b32_e32 v27, 0xffff0000, v30
	v_lshlrev_b32_e32 v26, 16, v30
	s_nop 0
	s_nop 0
	v_pk_fma_f32 v[20:21], v[28:29], v[48:49], v[20:21]
	v_pk_fma_f32 v[6:7], v[240:241], v[40:41], v[6:7]
	s_waitcnt vmcnt(1)
	v_pk_fma_f32 v[4:5], v[242:243], v[8:9], v[4:5]
	s_waitcnt vmcnt(0)
	v_pk_fma_f32 v[22:23], v[246:247], v[26:27], v[22:23]
	ds_read_u16 v27, v101 offset:1536
	ds_read_u16 v31, v101 offset:4608
	v_and_b32_e32 v30, 0xffff0000, v226
	v_lshlrev_b32_e32 v0, 16, v226
	v_mul_f32_e32 v26, 0xbfb8aa3b, v0
	s_waitcnt lgkmcnt(1)
	v_lshlrev_b32_e32 v54, 16, v27
	v_mul_f32_e32 v27, 0xbfb8aa3b, v30
	v_exp_f32_e32 v26, v26
	v_exp_f32_e32 v27, v27
	s_waitcnt lgkmcnt(0)
	v_lshlrev_b32_e32 v55, 16, v31
	v_pk_mul_f32 v[22:23], v[22:23], v[54:55]
	v_pk_fma_f32 v[20:21], v[248:249], v[24:25], v[20:21]
	v_pk_add_f32 v[26:27], v[26:27], 1.0 op_sel_hi:[1,0]
	v_and_b32_e32 v16, 0xffff0000, v228
	v_div_scale_f32 v31, s[20:21], v27, v27, v30
	v_rcp_f32_e32 v53, v31
	v_lshlrev_b32_e32 v2, 16, v228
	v_mul_f32_e32 v8, 0xbfb8aa3b, v2
	v_exp_f32_e32 v8, v8
	v_fma_f32 v54, -v31, v53, 1.0
	v_fmac_f32_e32 v53, v54, v53
	v_div_scale_f32 v54, vcc, v30, v27, v30
	v_mul_f32_e32 v55, v54, v53
	v_fma_f32 v56, -v31, v55, v54
	v_fmac_f32_e32 v55, v56, v53
	v_fma_f32 v31, -v31, v55, v54
	v_div_fmas_f32 v31, v31, v53, v55
	v_div_fixup_f32 v27, v31, v27, v30
	v_div_scale_f32 v30, s[20:21], v26, v26, v0
	v_rcp_f32_e32 v31, v30
	s_nop 0
	v_fma_f32 v53, -v30, v31, 1.0
	v_fmac_f32_e32 v31, v53, v31
	v_div_scale_f32 v53, vcc, v0, v26, v0
	v_mul_f32_e32 v54, v53, v31
	v_fma_f32 v55, -v30, v54, v53
	v_fmac_f32_e32 v54, v55, v31
	v_fma_f32 v30, -v30, v54, v53
	v_div_fmas_f32 v30, v30, v31, v54
	v_div_fixup_f32 v26, v30, v26, v0
	v_pk_mul_f32 v[22:23], v[26:27], v[22:23]
	v_and_b32_e32 v26, 0xffff0000, v227
	v_lshlrev_b32_e32 v27, 16, v227
	ds_read_u16 v1, v101 offset:7680
	ds_read_u16 v24, v101 offset:10752
	v_mul_f32_e32 v0, 0xbfb8aa3b, v27
	v_exp_f32_e32 v0, v0
	ds_read_u16 v9, v101 offset:13824
	ds_read_u16 v12, v101 offset:16896
	s_waitcnt lgkmcnt(2)
	v_lshlrev_b32_e32 v25, 16, v24
	v_lshlrev_b32_e32 v24, 16, v1
	v_mul_f32_e32 v1, 0xbfb8aa3b, v26
	v_exp_f32_e32 v1, v1
	v_pk_mul_f32 v[20:21], v[20:21], v[24:25]
	s_waitcnt lgkmcnt(0)
	v_lshlrev_b32_e32 v13, 16, v12
	v_lshlrev_b32_e32 v12, 16, v9
	v_pk_add_f32 v[0:1], v[0:1], 1.0 op_sel_hi:[1,0]
	v_mul_f32_e32 v9, 0xbfb8aa3b, v16
	v_div_scale_f32 v24, s[20:21], v1, v1, v26
	v_rcp_f32_e32 v25, v24
	v_exp_f32_e32 v9, v9
	v_pk_mul_f32 v[4:5], v[4:5], v[12:13]
	v_fma_f32 v28, -v24, v25, 1.0
	v_fmac_f32_e32 v25, v28, v25
	v_div_scale_f32 v28, vcc, v26, v1, v26
	v_mul_f32_e32 v29, v28, v25
	v_fma_f32 v30, -v24, v29, v28
	v_fmac_f32_e32 v29, v30, v25
	v_fma_f32 v24, -v24, v29, v28
	v_div_fmas_f32 v24, v24, v25, v29
	v_div_fixup_f32 v1, v24, v1, v26
	v_div_scale_f32 v24, s[20:21], v0, v0, v27
	v_rcp_f32_e32 v25, v24
	v_pk_add_f32 v[8:9], v[8:9], 1.0 op_sel_hi:[1,0]
	v_fma_f32 v26, -v24, v25, 1.0
	v_fmac_f32_e32 v25, v26, v25
	v_div_scale_f32 v26, vcc, v27, v0, v27
	v_div_scale_f32 v12, s[20:21], v9, v9, v16
	v_mul_f32_e32 v28, v26, v25
	v_rcp_f32_e32 v13, v12
	v_fma_f32 v29, -v24, v28, v26
	v_fmac_f32_e32 v28, v29, v25
	v_fma_f32 v24, -v24, v28, v26
	v_div_fmas_f32 v24, v24, v25, v28
	v_fma_f32 v17, -v12, v13, 1.0
	v_div_fixup_f32 v0, v24, v0, v27
	v_fmac_f32_e32 v13, v17, v13
	v_div_scale_f32 v17, vcc, v16, v9, v16
	v_pk_mul_f32 v[0:1], v[0:1], v[20:21]
	v_mul_f32_e32 v20, v17, v13
	v_fma_f32 v21, -v12, v20, v17
	v_fmac_f32_e32 v20, v21, v13
	v_fma_f32 v12, -v12, v20, v17
	v_div_fmas_f32 v12, v12, v13, v20
	v_div_fixup_f32 v9, v12, v9, v16
	v_div_scale_f32 v12, s[20:21], v8, v8, v2
	v_rcp_f32_e32 v13, v12
	s_nop 0
	v_fma_f32 v16, -v12, v13, 1.0
	v_fmac_f32_e32 v13, v16, v13
	v_div_scale_f32 v16, vcc, v2, v8, v2
	v_mul_f32_e32 v17, v16, v13
	v_fma_f32 v20, -v12, v17, v16
	v_fmac_f32_e32 v17, v20, v13
	v_fma_f32 v12, -v12, v17, v16
	v_div_fmas_f32 v12, v12, v13, v17
	v_div_fixup_f32 v8, v12, v8, v2
	v_pk_mul_f32 v[4:5], v[8:9], v[4:5]
	v_and_b32_e32 v9, 0xffff0000, v50
	v_lshlrev_b32_e32 v8, 16, v50
	v_pk_fma_f32 v[6:7], v[244:245], v[8:9], v[6:7]
	ds_read_u16 v3, v101 offset:19968
	ds_read_u16 v8, v101 offset:23040
	v_mul_f32_e32 v2, 0xbfb8aa3b, v11
	v_exp_f32_e32 v2, v2
	s_waitcnt lgkmcnt(0)
	v_lshlrev_b32_e32 v9, 16, v8
	v_lshlrev_b32_e32 v8, 16, v3
	v_mul_f32_e32 v3, 0xbfb8aa3b, v10
	v_exp_f32_e32 v3, v3
	v_pk_mul_f32 v[6:7], v[6:7], v[8:9]
	v_pk_add_f32 v[2:3], v[2:3], 1.0 op_sel_hi:[1,0]
	s_nop 0
	v_div_scale_f32 v8, s[20:21], v3, v3, v10
	v_rcp_f32_e32 v9, v8
	s_nop 0
	v_fma_f32 v12, -v8, v9, 1.0
	v_fmac_f32_e32 v9, v12, v9
	v_div_scale_f32 v12, vcc, v10, v3, v10
	v_mul_f32_e32 v13, v12, v9
	v_fma_f32 v14, -v8, v13, v12
	v_fmac_f32_e32 v13, v14, v9
	v_fma_f32 v8, -v8, v13, v12
	v_div_fmas_f32 v8, v8, v9, v13
	v_div_fixup_f32 v3, v8, v3, v10
	v_div_scale_f32 v8, s[20:21], v2, v2, v11
	v_rcp_f32_e32 v9, v8
	s_nop 0
	v_fma_f32 v10, -v8, v9, 1.0
	v_fmac_f32_e32 v9, v10, v9
	v_div_scale_f32 v10, vcc, v11, v2, v11
	v_mul_f32_e32 v12, v10, v9
	v_fma_f32 v13, -v8, v12, v10
	v_fmac_f32_e32 v12, v13, v9
	v_fma_f32 v8, -v8, v12, v10
	v_div_fmas_f32 v8, v8, v9, v12
	v_div_fixup_f32 v2, v8, v2, v11
	v_pk_mul_f32 v[2:3], v[2:3], v[6:7]
	v_cvt_pk_bf16_f32 v4, v4, v5
	v_cvt_pk_bf16_f32 v2, v2, v3
	v_mov_b32_e32 v3, v2
	v_mov_b32_e32 v2, v4
	v_lshlrev_b64 v[4:5], 12, v[34:35]
	v_lshl_add_u64 v[4:5], s[30:31], 0, v[4:5]
	v_bfe_u32 v12, v23, 16, 1
	v_bfe_u32 v13, v22, 16, 1
	v_lshl_add_u64 v[4:5], v[4:5], 0, s[70:71]
	v_add3_u32 v13, v22, v13, s94
	v_add3_u32 v12, v23, v12, s94
	v_cvt_pk_bf16_f32 v0, v0, v1
	v_add_co_u32_e32 v4, vcc, s22, v4
	v_mov_b32_e32 v1, v0
	v_perm_b32 v0, v12, v13, s95
	v_addc_co_u32_e32 v5, vcc, 0, v5, vcc
	global_store_dwordx4 v[4:5], v[0:3], off offset:3072
	v_mov_b32_e32 v15, v241
	v_mov_b32_e32 v18, v244
	v_mov_b32_e32 v19, v245
	v_mov_b32_e32 v32, v248
	v_mov_b32_e32 v33, v249
	v_add_u32_e32 v34, s19, v120
	v_ashrrev_i32_e32 v35, 31, v34
	v_lshl_add_u64 v[0:1], v[102:103], 0, s[70:71]
	v_add_co_u32_e32 v0, vcc, s3, v0
	s_nop 1
	v_addc_co_u32_e32 v1, vcc, 0, v1, vcc
	global_load_dwordx4 v[0:3], v[0:1], off offset:2048
	s_waitcnt vmcnt(1)
	v_lshl_add_u64 v[206:207], v[104:105], 0, s[70:71]
	v_add_co_u32_e32 v206, vcc, s3, v206
	s_nop 1
	v_addc_co_u32_e32 v207, vcc, 0, v207, vcc
	global_load_dwordx4 v[208:211], v[206:207], off offset:2048
	v_lshl_add_u64 v[214:215], v[106:107], 0, s[70:71]
	v_add_co_u32_e32 v214, vcc, s3, v214
	s_nop 1
	v_addc_co_u32_e32 v215, vcc, 0, v215, vcc
	global_load_dwordx4 v[216:219], v[214:215], off offset:2048
	v_mad_i64_i32 v[222:223], s[20:21], v34, s0, v[36:37]
	v_lshl_add_u64 v[224:225], v[222:223], 0, s[70:71]
	v_add_co_u32_e32 v224, vcc, s23, v224
	s_nop 1
	v_addc_co_u32_e32 v225, vcc, 0, v225, vcc
	global_load_dwordx4 v[226:229], v[224:225], off
	global_load_dwordx4 v[230:233], v161, s[84:85] offset:2064
	global_load_dwordx4 v[18:21], v161, s[84:85] offset:2048
	global_load_dwordx4 v[234:237], v161, s[86:87] offset:2064
	global_load_dwordx4 v[22:25], v161, s[86:87] offset:2048
	global_load_dwordx4 v[238:241], v161, s[36:37] offset:16
	global_load_dwordx4 v[26:29], v196, s[86:87]
	global_load_dwordx4 v[242:245], v161, s[38:39] offset:16
	global_load_dwordx4 v[246:249], v197, s[86:87] offset:2048
	s_waitcnt vmcnt(11)
	v_cndmask_b32_e64 v6, 0, v1, s[44:45]
	v_cndmask_b32_e64 v7, 0, v0, s[44:45]
	s_nop 0
	s_nop 0
	v_cndmask_b32_e64 v4, 0, v3, s[44:45]
	s_nop 0
	s_nop 0
	v_cndmask_b32_e64 v5, 0, v2, s[44:45]
	s_nop 0
	v_and_b32_e32 v13, 0xffff0000, v7
	v_lshlrev_b32_e32 v12, 16, v7
	v_and_b32_e32 v45, 0xffff0000, v6
	v_lshlrev_b32_e32 v44, 16, v6
	v_and_b32_e32 v41, 0xffff0000, v5
	v_lshlrev_b32_e32 v40, 16, v5
	s_waitcnt vmcnt(10)
	v_cndmask_b32_e64 v10, 0, v209, s[46:47]
	v_cndmask_b32_e64 v11, 0, v208, s[46:47]
	s_nop 0
	s_nop 0
	v_cndmask_b32_e64 v8, 0, v211, s[46:47]
	s_nop 0
	s_nop 0
	v_cndmask_b32_e64 v9, 0, v210, s[46:47]
	s_nop 0
	v_and_b32_e32 v17, 0xffff0000, v11
	v_lshlrev_b32_e32 v16, 16, v11
	v_and_b32_e32 v47, 0xffff0000, v10
	v_lshlrev_b32_e32 v46, 16, v10
	v_and_b32_e32 v43, 0xffff0000, v9
	v_lshlrev_b32_e32 v42, 16, v9
	v_and_b32_e32 v39, 0xffff0000, v8
	v_lshlrev_b32_e32 v38, 16, v8
	s_waitcnt vmcnt(9)
	v_cndmask_b32_e64 v50, 0, v217, s[52:53]
	v_cndmask_b32_e64 v30, 0, v216, s[52:53]
	s_nop 0
	s_nop 0
	s_nop 0
	v_cndmask_b32_e64 v48, 0, v219, s[52:53]
	s_nop 0
	s_nop 0
	v_cndmask_b32_e64 v49, 0, v218, s[52:53]
	s_nop 0
	v_and_b32_e32 v37, 0xffff0000, v4
	v_lshlrev_b32_e32 v36, 16, v4
	s_nop 0
	s_nop 0
	s_nop 0
	s_nop 0
	s_waitcnt vmcnt(5)
	v_pk_fma_f32 v[4:5], v[234:235], v[40:41], v[230:231]
	s_waitcnt vmcnt(4)
	v_pk_fma_f32 v[18:19], v[22:23], v[12:13], v[18:19]
	s_nop 0
	s_nop 0
	v_pk_fma_f32 v[20:21], v[24:25], v[44:45], v[20:21]
	v_and_b32_e32 v25, 0xffff0000, v50
	v_lshlrev_b32_e32 v24, 16, v50
	v_and_b32_e32 v9, 0xffff0000, v49
	v_lshlrev_b32_e32 v8, 16, v49
	v_pk_fma_f32 v[6:7], v[236:237], v[36:37], v[232:233]
	s_waitcnt vmcnt(3)
	v_pk_fma_f32 v[4:5], v[238:239], v[42:43], v[4:5]
	s_waitcnt vmcnt(2)
	v_pk_fma_f32 v[22:23], v[26:27], v[16:17], v[18:19]
	v_and_b32_e32 v27, 0xffff0000, v30
	v_lshlrev_b32_e32 v26, 16, v30
	s_nop 0
	s_nop 0
	v_pk_fma_f32 v[20:21], v[28:29], v[46:47], v[20:21]
	v_pk_fma_f32 v[6:7], v[240:241], v[38:39], v[6:7]
	s_waitcnt vmcnt(1)
	v_pk_fma_f32 v[4:5], v[242:243], v[8:9], v[4:5]
	s_waitcnt vmcnt(0)
	v_pk_fma_f32 v[22:23], v[246:247], v[26:27], v[22:23]
	ds_read_u16 v27, v101 offset:2048
	ds_read_u16 v31, v101 offset:5120
	v_and_b32_e32 v30, 0xffff0000, v226
	v_lshlrev_b32_e32 v0, 16, v226
	v_mul_f32_e32 v26, 0xbfb8aa3b, v0
	s_waitcnt lgkmcnt(1)
	v_lshlrev_b32_e32 v52, 16, v27
	v_mul_f32_e32 v27, 0xbfb8aa3b, v30
	v_exp_f32_e32 v26, v26
	v_exp_f32_e32 v27, v27
	s_waitcnt lgkmcnt(0)
	v_lshlrev_b32_e32 v53, 16, v31
	v_pk_mul_f32 v[22:23], v[22:23], v[52:53]
	v_pk_fma_f32 v[20:21], v[248:249], v[24:25], v[20:21]
	v_pk_add_f32 v[26:27], v[26:27], 1.0 op_sel_hi:[1,0]
	v_and_b32_e32 v25, 0xffff0000, v227
	v_div_scale_f32 v31, s[20:21], v27, v27, v30
	v_rcp_f32_e32 v51, v31
	v_lshlrev_b32_e32 v24, 16, v227
	v_and_b32_e32 v16, 0xffff0000, v228
	v_lshlrev_b32_e32 v2, 16, v228
	v_fma_f32 v52, -v31, v51, 1.0
	v_fmac_f32_e32 v51, v52, v51
	v_div_scale_f32 v52, vcc, v30, v27, v30
	v_mul_f32_e32 v53, v52, v51
	v_fma_f32 v54, -v31, v53, v52
	v_fmac_f32_e32 v53, v54, v51
	v_fma_f32 v31, -v31, v53, v52
	v_div_fmas_f32 v31, v31, v51, v53
	v_div_fixup_f32 v27, v31, v27, v30
	v_div_scale_f32 v30, s[20:21], v26, v26, v0
	v_rcp_f32_e32 v31, v30
	v_mul_f32_e32 v8, 0xbfb8aa3b, v2
	v_exp_f32_e32 v8, v8
	v_fma_f32 v51, -v30, v31, 1.0
	v_fmac_f32_e32 v31, v51, v31
	v_div_scale_f32 v51, vcc, v0, v26, v0
	v_mul_f32_e32 v52, v51, v31
	v_fma_f32 v53, -v30, v52, v51
	v_fmac_f32_e32 v52, v53, v31
	v_fma_f32 v30, -v30, v52, v51
	v_div_fmas_f32 v30, v30, v31, v52
	v_div_fixup_f32 v26, v30, v26, v0
	v_pk_mul_f32 v[22:23], v[26:27], v[22:23]
	ds_read_u16 v1, v101 offset:8192
	ds_read_u16 v26, v101 offset:11264
	v_mul_f32_e32 v0, 0xbfb8aa3b, v24
	v_exp_f32_e32 v0, v0
	ds_read_u16 v9, v101 offset:14336
	ds_read_u16 v12, v101 offset:17408
	s_waitcnt lgkmcnt(2)
	v_lshlrev_b32_e32 v27, 16, v26
	v_lshlrev_b32_e32 v26, 16, v1
	v_mul_f32_e32 v1, 0xbfb8aa3b, v25
	v_exp_f32_e32 v1, v1
	v_pk_mul_f32 v[20:21], v[20:21], v[26:27]
	s_waitcnt lgkmcnt(0)
	v_lshlrev_b32_e32 v13, 16, v12
	v_lshlrev_b32_e32 v12, 16, v9
	v_pk_add_f32 v[0:1], v[0:1], 1.0 op_sel_hi:[1,0]
	v_mul_f32_e32 v9, 0xbfb8aa3b, v16
	v_div_scale_f32 v26, s[20:21], v1, v1, v25
	v_rcp_f32_e32 v27, v26
	v_exp_f32_e32 v9, v9
	v_pk_mul_f32 v[4:5], v[4:5], v[12:13]
	v_fma_f32 v28, -v26, v27, 1.0
	v_fmac_f32_e32 v27, v28, v27
	v_div_scale_f32 v28, vcc, v25, v1, v25
	v_mul_f32_e32 v29, v28, v27
	v_fma_f32 v30, -v26, v29, v28
	v_fmac_f32_e32 v29, v30, v27
	v_fma_f32 v26, -v26, v29, v28
	v_div_fmas_f32 v26, v26, v27, v29
	v_div_fixup_f32 v1, v26, v1, v25
	v_div_scale_f32 v25, s[20:21], v0, v0, v24
	v_rcp_f32_e32 v26, v25
	v_pk_add_f32 v[8:9], v[8:9], 1.0 op_sel_hi:[1,0]
	v_fma_f32 v27, -v25, v26, 1.0
	v_fmac_f32_e32 v26, v27, v26
	v_div_scale_f32 v27, vcc, v24, v0, v24
	v_div_scale_f32 v12, s[20:21], v9, v9, v16
	v_mul_f32_e32 v28, v27, v26
	v_rcp_f32_e32 v13, v12
	v_fma_f32 v29, -v25, v28, v27
	v_fmac_f32_e32 v28, v29, v26
	v_fma_f32 v25, -v25, v28, v27
	v_div_fmas_f32 v25, v25, v26, v28
	v_fma_f32 v17, -v12, v13, 1.0
	v_div_fixup_f32 v0, v25, v0, v24
	v_fmac_f32_e32 v13, v17, v13
	v_div_scale_f32 v17, vcc, v16, v9, v16
	v_pk_mul_f32 v[0:1], v[0:1], v[20:21]
	v_mul_f32_e32 v20, v17, v13
	v_fma_f32 v21, -v12, v20, v17
	v_fmac_f32_e32 v20, v21, v13
	v_fma_f32 v12, -v12, v20, v17
	v_div_fmas_f32 v12, v12, v13, v20
	v_div_fixup_f32 v9, v12, v9, v16
	v_div_scale_f32 v12, s[20:21], v8, v8, v2
	v_rcp_f32_e32 v13, v12
	s_nop 0
	v_fma_f32 v16, -v12, v13, 1.0
	v_fmac_f32_e32 v13, v16, v13
	v_div_scale_f32 v16, vcc, v2, v8, v2
	v_mul_f32_e32 v17, v16, v13
	v_fma_f32 v20, -v12, v17, v16
	v_fmac_f32_e32 v17, v20, v13
	v_fma_f32 v12, -v12, v17, v16
	v_div_fmas_f32 v12, v12, v13, v17
	v_div_fixup_f32 v8, v12, v8, v2
	v_pk_mul_f32 v[4:5], v[8:9], v[4:5]
	v_and_b32_e32 v9, 0xffff0000, v48
	v_lshlrev_b32_e32 v8, 16, v48
	v_pk_fma_f32 v[6:7], v[244:245], v[8:9], v[6:7]
	v_and_b32_e32 v9, 0xffff0000, v229
	v_lshlrev_b32_e32 v8, 16, v229
	ds_read_u16 v3, v101 offset:20480
	ds_read_u16 v10, v101 offset:23552
	v_mul_f32_e32 v2, 0xbfb8aa3b, v8
	v_exp_f32_e32 v2, v2
	s_waitcnt lgkmcnt(0)
	v_lshlrev_b32_e32 v11, 16, v10
	v_lshlrev_b32_e32 v10, 16, v3
	v_mul_f32_e32 v3, 0xbfb8aa3b, v9
	v_exp_f32_e32 v3, v3
	v_pk_mul_f32 v[6:7], v[6:7], v[10:11]
	v_pk_add_f32 v[2:3], v[2:3], 1.0 op_sel_hi:[1,0]
	s_nop 0
	v_div_scale_f32 v10, s[20:21], v3, v3, v9
	v_rcp_f32_e32 v11, v10
	s_nop 0
	v_fma_f32 v12, -v10, v11, 1.0
	v_fmac_f32_e32 v11, v12, v11
	v_div_scale_f32 v12, vcc, v9, v3, v9
	v_mul_f32_e32 v13, v12, v11
	v_fma_f32 v14, -v10, v13, v12
	v_fmac_f32_e32 v13, v14, v11
	v_fma_f32 v10, -v10, v13, v12
	v_div_fmas_f32 v10, v10, v11, v13
	v_div_fixup_f32 v3, v10, v3, v9
	v_div_scale_f32 v9, s[20:21], v2, v2, v8
	v_rcp_f32_e32 v10, v9
	s_nop 0
	v_fma_f32 v11, -v9, v10, 1.0
	v_fmac_f32_e32 v10, v11, v10
	v_div_scale_f32 v11, vcc, v8, v2, v8
	v_mul_f32_e32 v12, v11, v10
	v_fma_f32 v13, -v9, v12, v11
	v_fmac_f32_e32 v12, v13, v10
	v_fma_f32 v9, -v9, v12, v11
	v_div_fmas_f32 v9, v9, v10, v12
	v_div_fixup_f32 v2, v9, v2, v8
	v_pk_mul_f32 v[2:3], v[2:3], v[6:7]
	v_cvt_pk_bf16_f32 v4, v4, v5
	v_cvt_pk_bf16_f32 v2, v2, v3
	v_mov_b32_e32 v3, v2
	v_mov_b32_e32 v2, v4
	v_lshlrev_b64 v[4:5], 12, v[34:35]
	v_lshl_add_u64 v[4:5], s[30:31], 0, v[4:5]
	v_bfe_u32 v12, v23, 16, 1
	v_bfe_u32 v13, v22, 16, 1
	v_lshl_add_u64 v[4:5], v[4:5], 0, s[70:71]
	v_add3_u32 v13, v22, v13, s94
	v_add3_u32 v12, v23, v12, s94
	v_cvt_pk_bf16_f32 v0, v0, v1
	v_add_co_u32_e32 v4, vcc, 0xcc00000, v4
	v_mov_b32_e32 v1, v0
	v_perm_b32 v0, v12, v13, s95
	v_addc_co_u32_e32 v5, vcc, 0, v5, vcc
	global_store_dwordx4 v[4:5], v[0:3], off offset:3072
	v_mov_b32_e32 v15, v241
	v_mov_b32_e32 v18, v244
	v_mov_b32_e32 v19, v245
	v_mov_b32_e32 v32, v248
	v_mov_b32_e32 v33, v249
	s_barrier
